# grid barrier leader: the vmcnt(0) before the XCD release moved off the local path (the release no longer waits for the leader's own L1 invalidate)
# speedup vs baseline: 1.0099x; 1.0052x over previous
.LBB0_736:
	s_or_b64 exec, exec, s[2:3]
	s_waitcnt vmcnt(0)
.Lbar_local:
	s_mov_b64 s[2:3], exec
	v_mbcnt_lo_u32_b32 v1, s2, 0
	v_mbcnt_hi_u32_b32 v1, s3, v1
	v_cmp_eq_u32_e32 vcc, 0, v1
	s_nop 1
	s_and_saveexec_b64 s[4:5], vcc
	s_cbranch_execz .LBB0_143
	s_bcnt1_i32_b64 s2, s[2:3]
	v_mov_b32_e32 v1, s2
	v_readlane_b32 s2, v254, 54
	v_readlane_b32 s3, v254, 55
	s_nop 4
	global_atomic_add v0, v1, s[2:3]
	s_branch .LBB0_143
